# v50 + P15 (final RMSNorm rows) rewritten: 4 ss values and all 32 row pieces of a unit loaded first, one wait, then scale + nt stores (was 32 dependent load->wait->store steps)
# speedup vs baseline: 1.0030x; 1.0030x over previous
; __device__ __forceinline__ float rstd_of(float ss) { return __builtin_amdgcn_rsqf(ss * (1.0f / 2048.0f) + NORM_EPS); }
; #define GAS __attribute__((address_space(1)))
; __device__ __forceinline__ void final_chain_phase(const float* H, const float* ss, const float* gf, float* out, const unsigned* ready, unsigned need, unsigned* tmo, int crot, int G, int wave) {
;     ...
;         __syncthreads();
; #pragma unroll
;         for (int r = 0; r < 4; ++r) { const int m = pm * 256 + slab * 32 + wave * 4 + r; const float rs = pg8::rstd_of(ss[m]);
;             const GAS f32x4* hr = (const GAS f32x4*)(H + (size_t)m * DM) + lane; GAS f32x4* orow = (GAS f32x4*)(out + (size_t)m * DM) + lane;
; #pragma unroll
;             for (int j = 0; j < 8; ++j) { const f32x4 v = hr[64 * j]; __builtin_nontemporal_store(v * rs * gq[j], orow + 64 * j); } }
.LBB0_1454:
	s_lshl_b32 s3, s10, 5
	s_and_b32 s3, s3, 0xe0
	s_lshl_b32 s2, s17, 8
	s_add_i32 s3, s3, s16
	s_add_i32 s2, s3, s2
	s_ashr_i32 s3, s2, 31
	s_lshl_b64 s[4:5], s[2:3], 2
	s_add_u32 s4, s11, s4
	s_addc_u32 s5, s12, s5
	s_waitcnt lgkmcnt(0)
	s_barrier
	global_load_dword v52, v38, s[4:5]
	s_lshl_b64 s[4:5], s[2:3], 13
	v_lshl_add_u64 v[46:47], v[32:33], 0, s[4:5]
	v_lshl_add_u64 v[56:57], v[34:35], 0, s[4:5]
	global_load_dwordx4 v[64:67], v[46:47], off
	global_load_dwordx4 v[68:71], v[46:47], off offset:1024
	global_load_dwordx4 v[72:75], v[46:47], off offset:2048
	global_load_dwordx4 v[76:79], v[46:47], off offset:3072
	v_add_co_u32_e32 v46, vcc, s15, v46
	s_nop 1
	v_addc_co_u32_e32 v47, vcc, 0, v47, vcc
	global_load_dwordx4 v[80:83], v[46:47], off
	global_load_dwordx4 v[84:87], v[46:47], off offset:1024
	global_load_dwordx4 v[88:91], v[46:47], off offset:2048
	global_load_dwordx4 v[92:95], v[46:47], off offset:3072
	s_or_b32 s4, s2, 1
	s_ashr_i32 s5, s4, 31
	s_lshl_b64 s[6:7], s[4:5], 2
	s_add_u32 s6, s11, s6
	s_addc_u32 s7, s12, s7
	global_load_dword v53, v38, s[6:7]
	s_lshl_b64 s[4:5], s[4:5], 13
	v_lshl_add_u64 v[46:47], v[32:33], 0, s[4:5]
	v_lshl_add_u64 v[58:59], v[34:35], 0, s[4:5]
	global_load_dwordx4 v[96:99], v[46:47], off
	global_load_dwordx4 v[100:103], v[46:47], off offset:1024
	global_load_dwordx4 v[104:107], v[46:47], off offset:2048
	global_load_dwordx4 v[108:111], v[46:47], off offset:3072
	v_add_co_u32_e32 v46, vcc, s15, v46
	s_nop 1
	v_addc_co_u32_e32 v47, vcc, 0, v47, vcc
	global_load_dwordx4 v[112:115], v[46:47], off
	global_load_dwordx4 v[116:119], v[46:47], off offset:1024
	global_load_dwordx4 v[120:123], v[46:47], off offset:2048
	global_load_dwordx4 v[124:127], v[46:47], off offset:3072
	s_or_b32 s4, s2, 2
	s_ashr_i32 s5, s4, 31
	s_lshl_b64 s[6:7], s[4:5], 2
	s_add_u32 s6, s11, s6
	s_addc_u32 s7, s12, s7
	global_load_dword v54, v38, s[6:7]
	s_lshl_b64 s[4:5], s[4:5], 13
	v_lshl_add_u64 v[46:47], v[32:33], 0, s[4:5]
	v_lshl_add_u64 v[60:61], v[34:35], 0, s[4:5]
	global_load_dwordx4 v[128:131], v[46:47], off
	global_load_dwordx4 v[132:135], v[46:47], off offset:1024
	global_load_dwordx4 v[136:139], v[46:47], off offset:2048
	global_load_dwordx4 v[140:143], v[46:47], off offset:3072
	v_add_co_u32_e32 v46, vcc, s15, v46
	s_nop 1
	v_addc_co_u32_e32 v47, vcc, 0, v47, vcc
	global_load_dwordx4 v[144:147], v[46:47], off
	global_load_dwordx4 v[148:151], v[46:47], off offset:1024
	global_load_dwordx4 v[152:155], v[46:47], off offset:2048
	global_load_dwordx4 v[156:159], v[46:47], off offset:3072
	s_or_b32 s4, s2, 3
	s_ashr_i32 s5, s4, 31
	s_lshl_b64 s[6:7], s[4:5], 2
	s_add_u32 s6, s11, s6
	s_addc_u32 s7, s12, s7
	global_load_dword v55, v38, s[6:7]
	s_lshl_b64 s[4:5], s[4:5], 13
	v_lshl_add_u64 v[46:47], v[32:33], 0, s[4:5]
	v_lshl_add_u64 v[62:63], v[34:35], 0, s[4:5]
	global_load_dwordx4 v[160:163], v[46:47], off
	global_load_dwordx4 v[164:167], v[46:47], off offset:1024
	global_load_dwordx4 v[168:171], v[46:47], off offset:2048
	global_load_dwordx4 v[172:175], v[46:47], off offset:3072
	v_add_co_u32_e32 v46, vcc, s15, v46
	s_nop 1
	v_addc_co_u32_e32 v47, vcc, 0, v47, vcc
	global_load_dwordx4 v[176:179], v[46:47], off
	global_load_dwordx4 v[180:183], v[46:47], off offset:1024
	global_load_dwordx4 v[184:187], v[46:47], off offset:2048
	global_load_dwordx4 v[188:191], v[46:47], off offset:3072
	s_waitcnt vmcnt(0)
	v_fmamk_f32 v52, v52, 0x3a000000, v40
	v_rsq_f32_e32 v192, v52
	v_fmamk_f32 v53, v53, 0x3a000000, v40
	v_rsq_f32_e32 v194, v53
	v_fmamk_f32 v54, v54, 0x3a000000, v40
	v_rsq_f32_e32 v196, v54
	v_fmamk_f32 v55, v55, 0x3a000000, v40
	v_rsq_f32_e32 v198, v55
	s_nop 0
	v_pk_mul_f32 v[64:65], v[64:65], v[192:193] op_sel_hi:[1,0]
	v_pk_mul_f32 v[66:67], v[66:67], v[192:193] op_sel_hi:[1,0]
	v_pk_mul_f32 v[64:65], v[0:1], v[64:65]
	v_pk_mul_f32 v[66:67], v[2:3], v[66:67]
	global_store_dwordx4 v[56:57], v[64:67], off nt
	v_pk_mul_f32 v[68:69], v[68:69], v[192:193] op_sel_hi:[1,0]
	v_pk_mul_f32 v[70:71], v[70:71], v[192:193] op_sel_hi:[1,0]
	v_pk_mul_f32 v[68:69], v[4:5], v[68:69]
	v_pk_mul_f32 v[70:71], v[6:7], v[70:71]
	global_store_dwordx4 v[56:57], v[68:71], off offset:1024 nt
	v_pk_mul_f32 v[72:73], v[72:73], v[192:193] op_sel_hi:[1,0]
	v_pk_mul_f32 v[74:75], v[74:75], v[192:193] op_sel_hi:[1,0]
	v_pk_mul_f32 v[72:73], v[8:9], v[72:73]
	v_pk_mul_f32 v[74:75], v[10:11], v[74:75]
	global_store_dwordx4 v[56:57], v[72:75], off offset:2048 nt
	v_pk_mul_f32 v[76:77], v[76:77], v[192:193] op_sel_hi:[1,0]
	v_pk_mul_f32 v[78:79], v[78:79], v[192:193] op_sel_hi:[1,0]
	v_pk_mul_f32 v[76:77], v[12:13], v[76:77]
	v_pk_mul_f32 v[78:79], v[14:15], v[78:79]
	global_store_dwordx4 v[56:57], v[76:79], off offset:3072 nt
	v_add_co_u32_e32 v56, vcc, s15, v56
	s_nop 1
	v_addc_co_u32_e32 v57, vcc, 0, v57, vcc
	v_pk_mul_f32 v[80:81], v[80:81], v[192:193] op_sel_hi:[1,0]
	v_pk_mul_f32 v[82:83], v[82:83], v[192:193] op_sel_hi:[1,0]
	v_pk_mul_f32 v[80:81], v[16:17], v[80:81]
	v_pk_mul_f32 v[82:83], v[18:19], v[82:83]
	global_store_dwordx4 v[56:57], v[80:83], off nt
	v_pk_mul_f32 v[84:85], v[84:85], v[192:193] op_sel_hi:[1,0]
	v_pk_mul_f32 v[86:87], v[86:87], v[192:193] op_sel_hi:[1,0]
	v_pk_mul_f32 v[84:85], v[20:21], v[84:85]
	v_pk_mul_f32 v[86:87], v[22:23], v[86:87]
	global_store_dwordx4 v[56:57], v[84:87], off offset:1024 nt
	v_pk_mul_f32 v[88:89], v[88:89], v[192:193] op_sel_hi:[1,0]
	v_pk_mul_f32 v[90:91], v[90:91], v[192:193] op_sel_hi:[1,0]
	v_pk_mul_f32 v[88:89], v[24:25], v[88:89]
	v_pk_mul_f32 v[90:91], v[26:27], v[90:91]
	global_store_dwordx4 v[56:57], v[88:91], off offset:2048 nt
	v_pk_mul_f32 v[92:93], v[92:93], v[192:193] op_sel_hi:[1,0]
; __device__ __forceinline__ float rstd_of(float ss) { return __builtin_amdgcn_rsqf(ss * (1.0f / 2048.0f) + NORM_EPS); }
; #define GAS __attribute__((address_space(1)))
; __device__ __forceinline__ void final_chain_phase(const float* H, const float* ss, const float* gf, float* out, const unsigned* ready, unsigned need, unsigned* tmo, int crot, int G, int wave) {
;     ...
;         for (int r = 0; r < 4; ++r) { const int m = pm * 256 + slab * 32 + wave * 4 + r; const float rs = pg8::rstd_of(ss[m]);
;             const GAS f32x4* hr = (const GAS f32x4*)(H + (size_t)m * DM) + lane; GAS f32x4* orow = (GAS f32x4*)(out + (size_t)m * DM) + lane;
; #pragma unroll
;             for (int j = 0; j < 8; ++j) { const f32x4 v = hr[64 * j]; __builtin_nontemporal_store(v * rs * gq[j], orow + 64 * j); } }
	v_pk_mul_f32 v[94:95], v[94:95], v[192:193] op_sel_hi:[1,0]
	v_pk_mul_f32 v[92:93], v[28:29], v[92:93]
	v_pk_mul_f32 v[94:95], v[30:31], v[94:95]
	global_store_dwordx4 v[56:57], v[92:95], off offset:3072 nt
	v_pk_mul_f32 v[96:97], v[96:97], v[194:195] op_sel_hi:[1,0]
	v_pk_mul_f32 v[98:99], v[98:99], v[194:195] op_sel_hi:[1,0]
	v_pk_mul_f32 v[96:97], v[0:1], v[96:97]
	v_pk_mul_f32 v[98:99], v[2:3], v[98:99]
	global_store_dwordx4 v[58:59], v[96:99], off nt
	v_pk_mul_f32 v[100:101], v[100:101], v[194:195] op_sel_hi:[1,0]
	v_pk_mul_f32 v[102:103], v[102:103], v[194:195] op_sel_hi:[1,0]
	v_pk_mul_f32 v[100:101], v[4:5], v[100:101]
	v_pk_mul_f32 v[102:103], v[6:7], v[102:103]
	global_store_dwordx4 v[58:59], v[100:103], off offset:1024 nt
	v_pk_mul_f32 v[104:105], v[104:105], v[194:195] op_sel_hi:[1,0]
	v_pk_mul_f32 v[106:107], v[106:107], v[194:195] op_sel_hi:[1,0]
	v_pk_mul_f32 v[104:105], v[8:9], v[104:105]
	v_pk_mul_f32 v[106:107], v[10:11], v[106:107]
	global_store_dwordx4 v[58:59], v[104:107], off offset:2048 nt
	v_pk_mul_f32 v[108:109], v[108:109], v[194:195] op_sel_hi:[1,0]
	v_pk_mul_f32 v[110:111], v[110:111], v[194:195] op_sel_hi:[1,0]
	v_pk_mul_f32 v[108:109], v[12:13], v[108:109]
	v_pk_mul_f32 v[110:111], v[14:15], v[110:111]
	global_store_dwordx4 v[58:59], v[108:111], off offset:3072 nt
	v_add_co_u32_e32 v58, vcc, s15, v58
	s_nop 1
	v_addc_co_u32_e32 v59, vcc, 0, v59, vcc
	v_pk_mul_f32 v[112:113], v[112:113], v[194:195] op_sel_hi:[1,0]
	v_pk_mul_f32 v[114:115], v[114:115], v[194:195] op_sel_hi:[1,0]
	v_pk_mul_f32 v[112:113], v[16:17], v[112:113]
	v_pk_mul_f32 v[114:115], v[18:19], v[114:115]
	global_store_dwordx4 v[58:59], v[112:115], off nt
	v_pk_mul_f32 v[116:117], v[116:117], v[194:195] op_sel_hi:[1,0]
	v_pk_mul_f32 v[118:119], v[118:119], v[194:195] op_sel_hi:[1,0]
	v_pk_mul_f32 v[116:117], v[20:21], v[116:117]
	v_pk_mul_f32 v[118:119], v[22:23], v[118:119]
	global_store_dwordx4 v[58:59], v[116:119], off offset:1024 nt
	v_pk_mul_f32 v[120:121], v[120:121], v[194:195] op_sel_hi:[1,0]
	v_pk_mul_f32 v[122:123], v[122:123], v[194:195] op_sel_hi:[1,0]
	v_pk_mul_f32 v[120:121], v[24:25], v[120:121]
	v_pk_mul_f32 v[122:123], v[26:27], v[122:123]
	global_store_dwordx4 v[58:59], v[120:123], off offset:2048 nt
	v_pk_mul_f32 v[124:125], v[124:125], v[194:195] op_sel_hi:[1,0]
	v_pk_mul_f32 v[126:127], v[126:127], v[194:195] op_sel_hi:[1,0]
	v_pk_mul_f32 v[124:125], v[28:29], v[124:125]
	v_pk_mul_f32 v[126:127], v[30:31], v[126:127]
	global_store_dwordx4 v[58:59], v[124:127], off offset:3072 nt
	v_pk_mul_f32 v[128:129], v[128:129], v[196:197] op_sel_hi:[1,0]
	v_pk_mul_f32 v[130:131], v[130:131], v[196:197] op_sel_hi:[1,0]
	v_pk_mul_f32 v[128:129], v[0:1], v[128:129]
	v_pk_mul_f32 v[130:131], v[2:3], v[130:131]
	global_store_dwordx4 v[60:61], v[128:131], off nt
	v_pk_mul_f32 v[132:133], v[132:133], v[196:197] op_sel_hi:[1,0]
	v_pk_mul_f32 v[134:135], v[134:135], v[196:197] op_sel_hi:[1,0]
	v_pk_mul_f32 v[132:133], v[4:5], v[132:133]
	v_pk_mul_f32 v[134:135], v[6:7], v[134:135]
	global_store_dwordx4 v[60:61], v[132:135], off offset:1024 nt
	v_pk_mul_f32 v[136:137], v[136:137], v[196:197] op_sel_hi:[1,0]
	v_pk_mul_f32 v[138:139], v[138:139], v[196:197] op_sel_hi:[1,0]
	v_pk_mul_f32 v[136:137], v[8:9], v[136:137]
	v_pk_mul_f32 v[138:139], v[10:11], v[138:139]
	global_store_dwordx4 v[60:61], v[136:139], off offset:2048 nt
	v_pk_mul_f32 v[140:141], v[140:141], v[196:197] op_sel_hi:[1,0]
	v_pk_mul_f32 v[142:143], v[142:143], v[196:197] op_sel_hi:[1,0]
	v_pk_mul_f32 v[140:141], v[12:13], v[140:141]
	v_pk_mul_f32 v[142:143], v[14:15], v[142:143]
	global_store_dwordx4 v[60:61], v[140:143], off offset:3072 nt
; __device__ __forceinline__ float rstd_of(float ss) { return __builtin_amdgcn_rsqf(ss * (1.0f / 2048.0f) + NORM_EPS); }
; #define GAS __attribute__((address_space(1)))
; __device__ __forceinline__ void final_chain_phase(const float* H, const float* ss, const float* gf, float* out, const unsigned* ready, unsigned need, unsigned* tmo, int crot, int G, int wave) {
;     ...
;     for (int l = crot; l < (MROWS / 256) * 8; l += G) {
;     ...
;         for (int r = 0; r < 4; ++r) { const int m = pm * 256 + slab * 32 + wave * 4 + r; const float rs = pg8::rstd_of(ss[m]);
;             const GAS f32x4* hr = (const GAS f32x4*)(H + (size_t)m * DM) + lane; GAS f32x4* orow = (GAS f32x4*)(out + (size_t)m * DM) + lane;
; #pragma unroll
;             for (int j = 0; j < 8; ++j) { const f32x4 v = hr[64 * j]; __builtin_nontemporal_store(v * rs * gq[j], orow + 64 * j); } }
	v_add_co_u32_e32 v60, vcc, s15, v60
	s_nop 1
	v_addc_co_u32_e32 v61, vcc, 0, v61, vcc
	v_pk_mul_f32 v[144:145], v[144:145], v[196:197] op_sel_hi:[1,0]
	v_pk_mul_f32 v[146:147], v[146:147], v[196:197] op_sel_hi:[1,0]
	v_pk_mul_f32 v[144:145], v[16:17], v[144:145]
	v_pk_mul_f32 v[146:147], v[18:19], v[146:147]
	global_store_dwordx4 v[60:61], v[144:147], off nt
	v_pk_mul_f32 v[148:149], v[148:149], v[196:197] op_sel_hi:[1,0]
	v_pk_mul_f32 v[150:151], v[150:151], v[196:197] op_sel_hi:[1,0]
	v_pk_mul_f32 v[148:149], v[20:21], v[148:149]
	v_pk_mul_f32 v[150:151], v[22:23], v[150:151]
	global_store_dwordx4 v[60:61], v[148:151], off offset:1024 nt
	v_pk_mul_f32 v[152:153], v[152:153], v[196:197] op_sel_hi:[1,0]
	v_pk_mul_f32 v[154:155], v[154:155], v[196:197] op_sel_hi:[1,0]
	v_pk_mul_f32 v[152:153], v[24:25], v[152:153]
	v_pk_mul_f32 v[154:155], v[26:27], v[154:155]
	global_store_dwordx4 v[60:61], v[152:155], off offset:2048 nt
	v_pk_mul_f32 v[156:157], v[156:157], v[196:197] op_sel_hi:[1,0]
	v_pk_mul_f32 v[158:159], v[158:159], v[196:197] op_sel_hi:[1,0]
	v_pk_mul_f32 v[156:157], v[28:29], v[156:157]
	v_pk_mul_f32 v[158:159], v[30:31], v[158:159]
	global_store_dwordx4 v[60:61], v[156:159], off offset:3072 nt
	v_pk_mul_f32 v[160:161], v[160:161], v[198:199] op_sel_hi:[1,0]
	v_pk_mul_f32 v[162:163], v[162:163], v[198:199] op_sel_hi:[1,0]
	v_pk_mul_f32 v[160:161], v[0:1], v[160:161]
	v_pk_mul_f32 v[162:163], v[2:3], v[162:163]
	global_store_dwordx4 v[62:63], v[160:163], off nt
	v_pk_mul_f32 v[164:165], v[164:165], v[198:199] op_sel_hi:[1,0]
	v_pk_mul_f32 v[166:167], v[166:167], v[198:199] op_sel_hi:[1,0]
	v_pk_mul_f32 v[164:165], v[4:5], v[164:165]
	v_pk_mul_f32 v[166:167], v[6:7], v[166:167]
	global_store_dwordx4 v[62:63], v[164:167], off offset:1024 nt
	v_pk_mul_f32 v[168:169], v[168:169], v[198:199] op_sel_hi:[1,0]
	v_pk_mul_f32 v[170:171], v[170:171], v[198:199] op_sel_hi:[1,0]
	v_pk_mul_f32 v[168:169], v[8:9], v[168:169]
	v_pk_mul_f32 v[170:171], v[10:11], v[170:171]
	global_store_dwordx4 v[62:63], v[168:171], off offset:2048 nt
	v_pk_mul_f32 v[172:173], v[172:173], v[198:199] op_sel_hi:[1,0]
	v_pk_mul_f32 v[174:175], v[174:175], v[198:199] op_sel_hi:[1,0]
	v_pk_mul_f32 v[172:173], v[12:13], v[172:173]
	v_pk_mul_f32 v[174:175], v[14:15], v[174:175]
	global_store_dwordx4 v[62:63], v[172:175], off offset:3072 nt
	v_add_co_u32_e32 v62, vcc, s15, v62
	s_nop 1
	v_addc_co_u32_e32 v63, vcc, 0, v63, vcc
	v_pk_mul_f32 v[176:177], v[176:177], v[198:199] op_sel_hi:[1,0]
	v_pk_mul_f32 v[178:179], v[178:179], v[198:199] op_sel_hi:[1,0]
	v_pk_mul_f32 v[176:177], v[16:17], v[176:177]
	v_pk_mul_f32 v[178:179], v[18:19], v[178:179]
	global_store_dwordx4 v[62:63], v[176:179], off nt
	v_pk_mul_f32 v[180:181], v[180:181], v[198:199] op_sel_hi:[1,0]
	v_pk_mul_f32 v[182:183], v[182:183], v[198:199] op_sel_hi:[1,0]
	v_pk_mul_f32 v[180:181], v[20:21], v[180:181]
	v_pk_mul_f32 v[182:183], v[22:23], v[182:183]
	global_store_dwordx4 v[62:63], v[180:183], off offset:1024 nt
	v_pk_mul_f32 v[184:185], v[184:185], v[198:199] op_sel_hi:[1,0]
	v_pk_mul_f32 v[186:187], v[186:187], v[198:199] op_sel_hi:[1,0]
	v_pk_mul_f32 v[184:185], v[24:25], v[184:185]
	v_pk_mul_f32 v[186:187], v[26:27], v[186:187]
	global_store_dwordx4 v[62:63], v[184:187], off offset:2048 nt
	v_pk_mul_f32 v[188:189], v[188:189], v[198:199] op_sel_hi:[1,0]
	v_pk_mul_f32 v[190:191], v[190:191], v[198:199] op_sel_hi:[1,0]
	v_pk_mul_f32 v[188:189], v[28:29], v[188:189]
	v_pk_mul_f32 v[190:191], v[30:31], v[190:191]
	global_store_dwordx4 v[62:63], v[188:191], off offset:3072 nt
	s_add_i32 s10, s10, s19
	s_cmpk_lt_i32 s10, 0x120
	s_cbranch_scc0 .LBB0_1467
